# P1 forget-gate cumsum: the 14 predicated prefix loads and the chunk pair load issued together with one wait instead of a wait after each
# baseline (speedup 1.0000x reference)
.LBB0_176:
	s_ashr_i32 s40, s55, 3
	s_ashr_i32 s41, s40, 31
	s_lshl_b64 s[42:43], s[40:41], 15
	s_add_u32 s42, s3, s42
	s_addc_u32 s43, s4, s43
	s_and_b32 s58, s53, 0x1c00
	v_mov_b32_e32 v238, 0
	v_mov_b32_e32 v239, 0
	v_mov_b32_e32 v240, 0
	v_mov_b32_e32 v241, 0
	v_mov_b32_e32 v242, 0
	v_mov_b32_e32 v243, 0
	v_mov_b32_e32 v244, 0
	v_mov_b32_e32 v245, 0
	v_mov_b32_e32 v246, 0
	v_mov_b32_e32 v247, 0
	v_mov_b32_e32 v248, 0
	v_mov_b32_e32 v249, 0
	v_mov_b32_e32 v250, 0
	v_mov_b32_e32 v251, 0
	v_cmp_gt_i32_e32 vcc, s58, v18
	v_lshl_add_u64 v[252:253], v[18:19], 2, s[42:43]
	s_and_saveexec_b64 s[44:45], vcc
	global_load_dword v238, v[252:253], off
	s_or_b64 exec, exec, s[44:45]
	v_cmp_gt_i32_e32 vcc, s58, v63
	s_and_saveexec_b64 s[44:45], vcc
	global_load_dword v239, v[252:253], off offset:2048
	s_or_b64 exec, exec, s[44:45]
	v_cmp_gt_i32_e32 vcc, s58, v22
	v_lshl_add_u64 v[252:253], v[22:23], 2, s[42:43]
	s_and_saveexec_b64 s[44:45], vcc
	global_load_dword v240, v[252:253], off
	s_or_b64 exec, exec, s[44:45]
	v_cmp_gt_i32_e32 vcc, s58, v24
	v_lshl_add_u64 v[252:253], v[24:25], 2, s[42:43]
	s_and_saveexec_b64 s[44:45], vcc
	global_load_dword v241, v[252:253], off
	s_or_b64 exec, exec, s[44:45]
	v_cmp_gt_i32_e32 vcc, s58, v26
	v_lshl_add_u64 v[252:253], v[26:27], 2, s[42:43]
	s_and_saveexec_b64 s[44:45], vcc
	global_load_dword v242, v[252:253], off
	s_or_b64 exec, exec, s[44:45]
	v_cmp_gt_i32_e32 vcc, s58, v28
	v_lshl_add_u64 v[252:253], v[28:29], 2, s[42:43]
	s_and_saveexec_b64 s[44:45], vcc
	global_load_dword v243, v[252:253], off
	s_or_b64 exec, exec, s[44:45]
	v_cmp_gt_i32_e32 vcc, s58, v30
	v_lshl_add_u64 v[252:253], v[30:31], 2, s[42:43]
	s_and_saveexec_b64 s[44:45], vcc
	global_load_dword v244, v[252:253], off
	s_or_b64 exec, exec, s[44:45]
	v_cmp_gt_i32_e32 vcc, s58, v32
	v_lshl_add_u64 v[252:253], v[32:33], 2, s[42:43]
	s_and_saveexec_b64 s[44:45], vcc
	global_load_dword v245, v[252:253], off
	s_or_b64 exec, exec, s[44:45]
	v_cmp_gt_i32_e32 vcc, s58, v34
	v_lshl_add_u64 v[252:253], v[34:35], 2, s[42:43]
	s_and_saveexec_b64 s[44:45], vcc
	global_load_dword v246, v[252:253], off
	s_or_b64 exec, exec, s[44:45]
	v_cmp_gt_i32_e32 vcc, s58, v36
	v_lshl_add_u64 v[252:253], v[36:37], 2, s[42:43]
	s_and_saveexec_b64 s[44:45], vcc
	global_load_dword v247, v[252:253], off
	s_or_b64 exec, exec, s[44:45]
	v_cmp_gt_i32_e32 vcc, s58, v38
	v_lshl_add_u64 v[252:253], v[38:39], 2, s[42:43]
	s_and_saveexec_b64 s[44:45], vcc
	global_load_dword v248, v[252:253], off
	s_or_b64 exec, exec, s[44:45]
	v_cmp_gt_i32_e32 vcc, s58, v40
	v_lshl_add_u64 v[252:253], v[40:41], 2, s[42:43]
	s_and_saveexec_b64 s[44:45], vcc
	global_load_dword v249, v[252:253], off
	s_or_b64 exec, exec, s[44:45]
	v_cmp_gt_i32_e32 vcc, s58, v42
	v_lshl_add_u64 v[252:253], v[42:43], 2, s[42:43]
	s_and_saveexec_b64 s[44:45], vcc
	global_load_dword v250, v[252:253], off
	s_or_b64 exec, exec, s[44:45]
	v_cmp_gt_i32_e32 vcc, s58, v44
	v_lshl_add_u64 v[252:253], v[44:45], 2, s[42:43]
	s_and_saveexec_b64 s[44:45], vcc
	global_load_dword v251, v[252:253], off
	s_or_b64 exec, exec, s[44:45]
	v_add_u32_e32 v252, s58, v20
	v_ashrrev_i32_e32 v253, 31, v252
	v_lshl_add_u64 v[252:253], v[252:253], 2, s[42:43]
	global_load_dwordx2 v[254:255], v[252:253], off
	s_waitcnt vmcnt(0)
	v_cvt_f64_f32_e32 v[4:5], v238
	v_add_f64 v[4:5], v[4:5], 0
	v_cvt_f64_f32_e32 v[2:3], v239
	v_cvt_f64_f32_e32 v[8:9], v240
	v_cvt_f64_f32_e32 v[6:7], v241
	v_cvt_f64_f32_e32 v[12:13], v242
	v_cvt_f64_f32_e32 v[10:11], v243
	v_cvt_f64_f32_e32 v[16:17], v244
	v_cvt_f64_f32_e32 v[14:15], v245
	v_cvt_f64_f32_e32 v[48:49], v246
	v_cvt_f64_f32_e32 v[46:47], v247
	v_cvt_f64_f32_e32 v[52:53], v248
	v_cvt_f64_f32_e32 v[50:51], v249
	v_cvt_f64_f32_e32 v[56:57], v250
	v_cvt_f64_f32_e32 v[54:55], v251
	v_add_f64 v[2:3], v[4:5], v[2:3]
	v_add_f64 v[2:3], v[2:3], v[8:9]
	v_add_f64 v[2:3], v[2:3], v[6:7]
	v_add_f64 v[2:3], v[2:3], v[12:13]
	v_add_f64 v[2:3], v[2:3], v[10:11]
	v_add_f64 v[2:3], v[2:3], v[16:17]
	v_add_f64 v[2:3], v[2:3], v[14:15]
	v_add_f64 v[2:3], v[2:3], v[48:49]
	v_add_f64 v[2:3], v[2:3], v[46:47]
	v_add_f64 v[2:3], v[2:3], v[52:53]
	v_add_f64 v[2:3], v[2:3], v[50:51]
	v_add_f64 v[2:3], v[2:3], v[56:57]
	v_add_f64 v[2:3], v[2:3], v[54:55]
	ds_bpermute_b32 v5, v1, v3
	ds_bpermute_b32 v4, v1, v2
	s_waitcnt lgkmcnt(0)
	v_add_f64 v[2:3], v[2:3], v[4:5]
	ds_bpermute_b32 v5, v58, v3
	ds_bpermute_b32 v4, v58, v2
	s_waitcnt lgkmcnt(0)
	v_add_f64 v[2:3], v[2:3], v[4:5]
	ds_bpermute_b32 v5, v59, v3
	ds_bpermute_b32 v4, v59, v2
	s_waitcnt lgkmcnt(0)
	v_add_f64 v[2:3], v[2:3], v[4:5]
	ds_bpermute_b32 v5, v60, v3
	ds_bpermute_b32 v4, v60, v2
	s_waitcnt lgkmcnt(0)
	v_add_f64 v[2:3], v[2:3], v[4:5]
	ds_bpermute_b32 v5, v61, v3
	ds_bpermute_b32 v4, v61, v2
	s_waitcnt lgkmcnt(0)
	v_add_f64 v[2:3], v[2:3], v[4:5]
	ds_bpermute_b32 v5, v62, v3
	ds_bpermute_b32 v4, v62, v2
	s_and_saveexec_b64 s[44:45], s[6:7]
	s_cbranch_execz .LBB0_206
	s_waitcnt lgkmcnt(0)
	v_add_f64 v[2:3], v[2:3], v[4:5]
	v_mov_b32_e32 v4, s52
	ds_write_b64 v4, v[2:3]
.LBB0_206:
	s_or_b64 exec, exec, s[44:45]
	v_add_u32_e32 v2, s58, v20
	v_ashrrev_i32_e32 v3, 31, v2
	v_lshl_add_u64 v[2:3], v[2:3], 2, s[42:43]
	s_waitcnt lgkmcnt(0)
	s_barrier
	v_mov_b32_e32 v2, v254
	v_mov_b32_e32 v3, v255
	s_waitcnt vmcnt(0)
	v_cvt_f64_f32_e32 v[48:49], v2
	v_cvt_f64_f32_e32 v[2:3], v3
	v_add_f64 v[46:47], v[48:49], v[2:3]
	ds_bpermute_b32 v3, v64, v47
	ds_bpermute_b32 v2, v64, v46
	s_waitcnt lgkmcnt(0)
	v_add_f64 v[2:3], v[46:47], v[2:3]
	v_cndmask_b32_e64 v3, v3, v47, s[6:7]
	v_cndmask_b32_e64 v2, v2, v46, s[6:7]
	ds_bpermute_b32 v5, v65, v3
	ds_bpermute_b32 v4, v65, v2
	s_waitcnt lgkmcnt(0)
	v_add_f64 v[4:5], v[2:3], v[4:5]
	v_cndmask_b32_e64 v3, v5, v3, s[10:11]
	v_cndmask_b32_e64 v2, v4, v2, s[10:11]
	ds_bpermute_b32 v5, v66, v3
	ds_bpermute_b32 v4, v66, v2
	s_waitcnt lgkmcnt(0)
	v_add_f64 v[4:5], v[2:3], v[4:5]
	v_cndmask_b32_e64 v3, v5, v3, s[12:13]
	v_cndmask_b32_e64 v2, v4, v2, s[12:13]
	ds_bpermute_b32 v5, v67, v3
	ds_bpermute_b32 v4, v67, v2
	s_waitcnt lgkmcnt(0)
	v_add_f64 v[4:5], v[2:3], v[4:5]
	v_cndmask_b32_e64 v11, v5, v3, s[14:15]
	v_cndmask_b32_e64 v10, v4, v2, s[14:15]
	ds_bpermute_b32 v13, v68, v11
	ds_bpermute_b32 v12, v68, v10
	ds_read_b128 v[6:9], v70
	ds_read_b128 v[2:5], v70 offset:16
	s_waitcnt lgkmcnt(2)
	v_add_f64 v[12:13], v[10:11], v[12:13]
	v_cndmask_b32_e64 v51, v13, v11, s[16:17]
	v_cndmask_b32_e64 v50, v12, v10, s[16:17]
	ds_bpermute_b32 v53, v69, v51
	ds_bpermute_b32 v52, v69, v50
	ds_read_b128 v[14:17], v70 offset:32
	ds_read_b128 v[10:13], v70 offset:48
	s_waitcnt lgkmcnt(2)
	v_add_f64 v[52:53], v[50:51], v[52:53]
	s_and_saveexec_b64 s[42:43], s[8:9]
	v_mov_b32_e32 v54, s52
	ds_write_b64 v54, v[52:53] offset:64
	s_or_b64 exec, exec, s[42:43]
	s_andn2_b64 vcc, exec, s[0:1]
	s_waitcnt lgkmcnt(0)
	s_barrier
	s_cbranch_vccnz .LBB0_223
	ds_read_b64 v[54:55], v70 offset:64
	s_waitcnt lgkmcnt(0)
	v_add_f64 v[54:55], v[54:55], 0
	s_andn2_b64 vcc, exec, s[20:21]
	s_cbranch_vccnz .LBB0_211

	.amdhsa_kernel _Z8yoco_fwd4Args
		.amdhsa_group_segment_fixed_size 0
		.amdhsa_private_segment_fixed_size 0
		.amdhsa_kernarg_size 416
		.amdhsa_user_sgpr_count 2
		.amdhsa_user_sgpr_dispatch_ptr 0
		.amdhsa_user_sgpr_queue_ptr 0
		.amdhsa_user_sgpr_kernarg_segment_ptr 1
		.amdhsa_user_sgpr_dispatch_id 0
		.amdhsa_user_sgpr_kernarg_preload_length 0
		.amdhsa_user_sgpr_kernarg_preload_offset 0
		.amdhsa_user_sgpr_private_segment_size 0
		.amdhsa_uses_dynamic_stack 0
		.amdhsa_enable_private_segment 0
		.amdhsa_system_sgpr_workgroup_id_x 1
		.amdhsa_system_sgpr_workgroup_id_y 0
		.amdhsa_system_sgpr_workgroup_id_z 0
		.amdhsa_system_sgpr_workgroup_info 0
		.amdhsa_system_vgpr_workitem_id 2
		.amdhsa_next_free_vgpr 256
		.amdhsa_next_free_sgpr 102
		.amdhsa_accum_offset 256
		.amdhsa_reserve_vcc 1
		.amdhsa_float_round_mode_32 0
		.amdhsa_float_round_mode_16_64 0
		.amdhsa_float_denorm_mode_32 3
		.amdhsa_float_denorm_mode_16_64 3
		.amdhsa_dx10_clamp 1
		.amdhsa_ieee_mode 1
		.amdhsa_fp16_overflow 0
		.amdhsa_tg_split 0
		.amdhsa_exception_fp_ieee_invalid_op 0
		.amdhsa_exception_fp_denorm_src 0
		.amdhsa_exception_fp_ieee_div_zero 0
		.amdhsa_exception_fp_ieee_overflow 0
		.amdhsa_exception_fp_ieee_underflow 0
		.amdhsa_exception_fp_ieee_inexact 0
		.amdhsa_exception_int_div_zero 0
	.end_amdhsa_kernel

amdhsa.kernels:
  - .agpr_count:     0
    .args:
      - .offset:         0
        .size:           160
        .value_kind:     by_value
      - .offset:         160
        .size:           4
        .value_kind:     hidden_block_count_x
      - .offset:         164
        .size:           4
        .value_kind:     hidden_block_count_y
      - .offset:         168
        .size:           4
        .value_kind:     hidden_block_count_z
      - .offset:         172
        .size:           2
        .value_kind:     hidden_group_size_x
      - .offset:         174
        .size:           2
        .value_kind:     hidden_group_size_y
      - .offset:         176
        .size:           2
        .value_kind:     hidden_group_size_z
      - .offset:         178
        .size:           2
        .value_kind:     hidden_remainder_x
      - .offset:         180
        .size:           2
        .value_kind:     hidden_remainder_y
      - .offset:         182
        .size:           2
        .value_kind:     hidden_remainder_z
      - .offset:         200
        .size:           8
        .value_kind:     hidden_global_offset_x
      - .offset:         208
        .size:           8
        .value_kind:     hidden_global_offset_y
      - .offset:         216
        .size:           8
        .value_kind:     hidden_global_offset_z
      - .offset:         224
        .size:           2
        .value_kind:     hidden_grid_dims
      - .offset:         248
        .size:           8
        .value_kind:     hidden_multigrid_sync_arg
      - .offset:         280
        .size:           4
        .value_kind:     hidden_dynamic_lds_size
    .group_segment_fixed_size: 0
    .kernarg_segment_align: 8
    .kernarg_segment_size: 416
    .language:       OpenCL C
    .language_version:
      - 2
      - 0
    .max_flat_workgroup_size: 512
    .name:           _Z8yoco_fwd4Args
    .private_segment_fixed_size: 0
    .sgpr_count:     108
    .sgpr_spill_count: 19
    .symbol:         _Z8yoco_fwd4Args.kd
    .uniform_work_group_size: 1
    .uses_dynamic_stack: false
    .vgpr_count:     256
    .vgpr_spill_count: 0
    .wavefront_size: 64
